# K=2 + early non-leader invalidate + flat release: non-leader workgroups poll the cross-XCD generation word directly instead of waiting for their XCD leader to forward it
# speedup vs baseline: 1.0328x; 1.0005x over previous
.LBB0_354:
	s_lshl_b32 s4, s97, 8
	s_add_u32 s4, s78, s4
	s_addc_u32 s5, s79, 0
	v_mov_b32_e32 v3, 0x1000
	v_mov_b32_e32 v5, 1
	global_atomic_add v5, v3, v5, s[4:5] offset:1024 sc0
	v_cvt_f32_u32_e32 v3, v4
	v_sub_u32_e32 v6, 0, v4
	v_rcp_iflag_f32_e32 v3, v3
	s_nop 0
	v_mul_f32_e32 v3, 0x4f7ffffe, v3
	v_cvt_u32_f32_e32 v3, v3
	v_mul_lo_u32 v6, v6, v3
	v_mul_hi_u32 v6, v3, v6
	v_add_u32_e32 v3, v3, v6
	s_waitcnt vmcnt(0)
	v_mul_hi_u32 v3, v5, v3
	v_mul_lo_u32 v6, v3, v4
	v_sub_u32_e32 v6, v5, v6
	v_add_u32_e32 v7, 1, v3
	v_cmp_ge_u32_e32 vcc, v6, v4
	v_add_u32_e32 v5, 1, v5
	s_nop 0
	v_cndmask_b32_e32 v3, v3, v7, vcc
	v_sub_u32_e32 v7, v6, v4
	v_cndmask_b32_e32 v6, v6, v7, vcc
	v_add_u32_e32 v7, 1, v3
	v_cmp_ge_u32_e32 vcc, v6, v4
	s_nop 1
	v_cndmask_b32_e32 v3, v3, v7, vcc
	v_mul_lo_u32 v6, v4, v3
	v_add_u32_e32 v4, v6, v4
	v_cmp_ne_u32_e32 vcc, v5, v4
	s_and_saveexec_b64 s[6:7], vcc
	s_xor_b64 s[6:7], exec, s[6:7]
	s_cbranch_execz .LBB0_368
	s_waitcnt lgkmcnt(0)
	buffer_inv sc1
	v_mov_b32_e32 v2, 0x3000
	global_load_dword v2, v2, s[78:79] offset:1280 sc1
	s_add_u32 s10, s78, 0x3500
	s_addc_u32 s11, s79, 0
	s_waitcnt vmcnt(0)
	v_cmp_eq_u32_e32 vcc, v2, v3
	s_and_saveexec_b64 s[8:9], vcc
	s_cbranch_execz .LBB0_367
	s_mov_b32 s26, 1
	s_mov_b64 s[12:13], 0
	v_mov_b32_e32 v2, 0
	s_branch .LBB0_358

.LBB0_1411:
	s_lshl_b32 s4, s97, 8
	s_add_u32 s4, s78, s4
	s_addc_u32 s5, s79, 0
	v_mov_b32_e32 v3, 0x1000
	v_mov_b32_e32 v5, 1
	global_atomic_add v5, v3, v5, s[4:5] offset:1024 sc0
	v_cvt_f32_u32_e32 v3, v4
	v_sub_u32_e32 v6, 0, v4
	v_rcp_iflag_f32_e32 v3, v3
	s_nop 0
	v_mul_f32_e32 v3, 0x4f7ffffe, v3
	v_cvt_u32_f32_e32 v3, v3
	v_mul_lo_u32 v6, v6, v3
	v_mul_hi_u32 v6, v3, v6
	v_add_u32_e32 v3, v3, v6
	s_waitcnt vmcnt(0)
	v_mul_hi_u32 v3, v5, v3
	v_mul_lo_u32 v6, v3, v4
	v_sub_u32_e32 v6, v5, v6
	v_add_u32_e32 v7, 1, v3
	v_cmp_ge_u32_e32 vcc, v6, v4
	v_add_u32_e32 v5, 1, v5
	s_nop 0
	v_cndmask_b32_e32 v3, v3, v7, vcc
	v_sub_u32_e32 v7, v6, v4
	v_cndmask_b32_e32 v6, v6, v7, vcc
	v_add_u32_e32 v7, 1, v3
	v_cmp_ge_u32_e32 vcc, v6, v4
	s_nop 1
	v_cndmask_b32_e32 v3, v3, v7, vcc
	v_mul_lo_u32 v6, v4, v3
	v_add_u32_e32 v4, v6, v4
	v_cmp_ne_u32_e32 vcc, v5, v4
	s_and_saveexec_b64 s[6:7], vcc
	s_xor_b64 s[6:7], exec, s[6:7]
	s_cbranch_execz .LBB0_1425
	s_waitcnt lgkmcnt(0)
	buffer_inv sc1
	v_mov_b32_e32 v2, 0x3000
	global_load_dword v2, v2, s[78:79] offset:1280 sc1
	s_add_u32 s10, s78, 0x3500
	s_addc_u32 s11, s79, 0
	s_waitcnt vmcnt(0)
	v_cmp_eq_u32_e32 vcc, v2, v3
	s_and_saveexec_b64 s[8:9], vcc
	s_cbranch_execz .LBB0_1424
	s_mov_b32 s22, 1
	s_mov_b64 s[12:13], 0
	v_mov_b32_e32 v2, 0
	s_branch .LBB0_1415
